# epi7 + attention: dropped the 16 post-asm s_nop 0 pads in front of QK^T/PV MFMAs whose operands come from ds_read (no VALU producer)
# speedup vs baseline: 1.0041x; 1.0004x over previous
.LBB0_403:
	ds_read_b64_tr_b16 v[146:147], v213 offset:0
	ds_read_b64_tr_b16 v[148:149], v213 offset:0x800
	ds_read_b64_tr_b16 v[150:151], v213 offset:0x1000
	ds_read_b64_tr_b16 v[152:153], v213 offset:0x1800
	ds_read_b64_tr_b16 v[154:155], v213 offset:0x2000
	ds_read_b64_tr_b16 v[156:157], v213 offset:0x2800
	ds_read_b64_tr_b16 v[158:159], v213 offset:0x3000
	ds_read_b64_tr_b16 v[160:161], v213 offset:0x3800
	s_waitcnt lgkmcnt(6)
	v_mfma_f32_32x32x16_bf16 v[114:129], v[130:133], v[146:149], v[114:129]
	ds_read_b64_tr_b16 v[218:219], v213 offset:0x200
	ds_read_b64_tr_b16 v[220:221], v213 offset:0xa00
	s_waitcnt lgkmcnt(6)
	v_mfma_f32_32x32x16_bf16 v[114:129], v[134:137], v[150:153], v[114:129]
	ds_read_b64_tr_b16 v[146:147], v213 offset:0x1200
	ds_read_b64_tr_b16 v[148:149], v213 offset:0x1a00
	s_waitcnt lgkmcnt(6)
	v_mfma_f32_32x32x16_bf16 v[114:129], v[138:141], v[154:157], v[114:129]
	ds_read_b64_tr_b16 v[150:151], v213 offset:0x2200
	ds_read_b64_tr_b16 v[152:153], v213 offset:0x2a00
	s_waitcnt lgkmcnt(6)
	v_mfma_f32_32x32x16_bf16 v[114:129], v[142:145], v[158:161], v[114:129]
	ds_read_b64_tr_b16 v[154:155], v213 offset:0x3200
	ds_read_b64_tr_b16 v[156:157], v213 offset:0x3a00
	s_waitcnt lgkmcnt(6)
	v_mfma_f32_32x32x16_bf16 v[98:113], v[130:133], v[218:221], v[98:113]
	ds_read_b64_tr_b16 v[158:159], v213 offset:0x400
	ds_read_b64_tr_b16 v[160:161], v213 offset:0xc00
	s_waitcnt lgkmcnt(6)
	v_mfma_f32_32x32x16_bf16 v[98:113], v[134:137], v[146:149], v[98:113]
	ds_read_b64_tr_b16 v[218:219], v213 offset:0x1400
	ds_read_b64_tr_b16 v[220:221], v213 offset:0x1c00
	s_waitcnt lgkmcnt(6)
	v_mfma_f32_32x32x16_bf16 v[98:113], v[138:141], v[150:153], v[98:113]
	ds_read_b64_tr_b16 v[146:147], v213 offset:0x2400
	ds_read_b64_tr_b16 v[148:149], v213 offset:0x2c00
	s_waitcnt lgkmcnt(6)
	v_mfma_f32_32x32x16_bf16 v[98:113], v[142:145], v[154:157], v[98:113]
	ds_read_b64_tr_b16 v[150:151], v213 offset:0x3400
	ds_read_b64_tr_b16 v[152:153], v213 offset:0x3c00
	s_waitcnt lgkmcnt(6)
	v_mfma_f32_32x32x16_bf16 v[82:97], v[130:133], v[158:161], v[82:97]
	ds_read_b64_tr_b16 v[154:155], v213 offset:0x600
	ds_read_b64_tr_b16 v[156:157], v213 offset:0xe00
	s_waitcnt lgkmcnt(6)
	v_mfma_f32_32x32x16_bf16 v[82:97], v[134:137], v[218:221], v[82:97]
	ds_read_b64_tr_b16 v[158:159], v213 offset:0x1600
	ds_read_b64_tr_b16 v[160:161], v213 offset:0x1e00
	s_waitcnt lgkmcnt(6)
	v_mfma_f32_32x32x16_bf16 v[82:97], v[138:141], v[146:149], v[82:97]
	ds_read_b64_tr_b16 v[218:219], v213 offset:0x2600
	ds_read_b64_tr_b16 v[220:221], v213 offset:0x2e00
	s_waitcnt lgkmcnt(6)
	v_mfma_f32_32x32x16_bf16 v[82:97], v[142:145], v[150:153], v[82:97]
	ds_read_b64_tr_b16 v[146:147], v213 offset:0x3600
	ds_read_b64_tr_b16 v[148:149], v213 offset:0x3e00
	s_waitcnt lgkmcnt(6)
	v_mfma_f32_32x32x16_bf16 v[66:81], v[130:133], v[154:157], v[66:81]
	ds_read_b64_tr_b16 v[150:151], v213 offset:0x4000
	ds_read_b64_tr_b16 v[152:153], v213 offset:0x4800
	s_waitcnt lgkmcnt(6)
	v_mfma_f32_32x32x16_bf16 v[66:81], v[134:137], v[158:161], v[66:81]
	ds_read_b64_tr_b16 v[154:155], v213 offset:0x5000
	ds_read_b64_tr_b16 v[156:157], v213 offset:0x5800
	s_waitcnt lgkmcnt(6)
	v_mfma_f32_32x32x16_bf16 v[66:81], v[138:141], v[218:221], v[66:81]
	ds_read_b64_tr_b16 v[158:159], v213 offset:0x6000
	ds_read_b64_tr_b16 v[160:161], v213 offset:0x6800
	s_waitcnt lgkmcnt(6)
	v_mfma_f32_32x32x16_bf16 v[66:81], v[142:145], v[146:149], v[66:81]
	ds_read_b64_tr_b16 v[218:219], v213 offset:0x7000
	ds_read_b64_tr_b16 v[220:221], v213 offset:0x7800
	s_waitcnt lgkmcnt(6)
	v_mfma_f32_32x32x16_bf16 v[50:65], v[130:133], v[150:153], v[50:65]
	ds_read_b64_tr_b16 v[146:147], v213 offset:0x4200
	ds_read_b64_tr_b16 v[148:149], v213 offset:0x4a00
	s_waitcnt lgkmcnt(6)
	v_mfma_f32_32x32x16_bf16 v[50:65], v[134:137], v[154:157], v[50:65]
	ds_read_b64_tr_b16 v[150:151], v213 offset:0x5200
	ds_read_b64_tr_b16 v[152:153], v213 offset:0x5a00
	s_waitcnt lgkmcnt(6)
	v_mfma_f32_32x32x16_bf16 v[50:65], v[138:141], v[158:161], v[50:65]
	ds_read_b64_tr_b16 v[154:155], v213 offset:0x6200
	ds_read_b64_tr_b16 v[156:157], v213 offset:0x6a00
	s_waitcnt lgkmcnt(6)
	v_mfma_f32_32x32x16_bf16 v[50:65], v[142:145], v[218:221], v[50:65]
	ds_read_b64_tr_b16 v[158:159], v213 offset:0x7200
	ds_read_b64_tr_b16 v[160:161], v213 offset:0x7a00
	s_waitcnt lgkmcnt(6)
	v_mfma_f32_32x32x16_bf16 v[34:49], v[130:133], v[146:149], v[34:49]
	ds_read_b64_tr_b16 v[218:219], v213 offset:0x4400
	ds_read_b64_tr_b16 v[220:221], v213 offset:0x4c00
	s_waitcnt lgkmcnt(6)
	v_mfma_f32_32x32x16_bf16 v[34:49], v[134:137], v[150:153], v[34:49]
	ds_read_b64_tr_b16 v[146:147], v213 offset:0x5400
	ds_read_b64_tr_b16 v[148:149], v213 offset:0x5c00
	s_waitcnt lgkmcnt(6)
	v_mfma_f32_32x32x16_bf16 v[34:49], v[138:141], v[154:157], v[34:49]
	ds_read_b64_tr_b16 v[150:151], v213 offset:0x6400
	ds_read_b64_tr_b16 v[152:153], v213 offset:0x6c00
	s_waitcnt lgkmcnt(6)
	v_mfma_f32_32x32x16_bf16 v[34:49], v[142:145], v[158:161], v[34:49]
	ds_read_b64_tr_b16 v[154:155], v213 offset:0x7400
	ds_read_b64_tr_b16 v[156:157], v213 offset:0x7c00
	s_waitcnt lgkmcnt(6)
	v_mfma_f32_32x32x16_bf16 v[18:33], v[130:133], v[218:221], v[18:33]
	ds_read_b64_tr_b16 v[158:159], v213 offset:0x4600
	ds_read_b64_tr_b16 v[160:161], v213 offset:0x4e00
	s_waitcnt lgkmcnt(6)
	v_mfma_f32_32x32x16_bf16 v[18:33], v[134:137], v[146:149], v[18:33]
	ds_read_b64_tr_b16 v[218:219], v213 offset:0x5600
	ds_read_b64_tr_b16 v[220:221], v213 offset:0x5e00
	s_waitcnt lgkmcnt(6)
	v_mfma_f32_32x32x16_bf16 v[18:33], v[138:141], v[150:153], v[18:33]
	ds_read_b64_tr_b16 v[146:147], v213 offset:0x6600
	ds_read_b64_tr_b16 v[148:149], v213 offset:0x6e00
	s_waitcnt lgkmcnt(6)
	v_mfma_f32_32x32x16_bf16 v[18:33], v[142:145], v[154:157], v[18:33]
	ds_read_b64_tr_b16 v[150:151], v213 offset:0x7600
	ds_read_b64_tr_b16 v[152:153], v213 offset:0x7e00
	s_waitcnt lgkmcnt(6)
	v_mfma_f32_32x32x16_bf16 v[2:17], v[130:133], v[158:161], v[2:17]
	s_waitcnt lgkmcnt(4)
	v_mfma_f32_32x32x16_bf16 v[2:17], v[134:137], v[218:221], v[2:17]
	s_waitcnt lgkmcnt(2)
	v_mfma_f32_32x32x16_bf16 v[2:17], v[138:141], v[146:149], v[2:17]
	s_waitcnt lgkmcnt(0)
	v_mfma_f32_32x32x16_bf16 v[2:17], v[142:145], v[150:153], v[2:17]
	v_add_u32_e32 v242, s38, v208
	ds_read_b128 v[130:133], v242 offset:0
	ds_read_b128 v[134:137], v242 offset:0x2000
	v_add_u32_e32 v243, s38, v209
	ds_read_b128 v[218:221], v243 offset:0
	ds_read_b128 v[222:225], v243 offset:0x2000
	v_add_u32_e32 v244, s38, v210
	ds_read_b128 v[226:229], v244 offset:0
	ds_read_b128 v[230:233], v244 offset:0x2000
	s_waitcnt lgkmcnt(4)
	v_add_u32_e32 v245, s38, v211
	v_mfma_f32_32x32x16_bf16 v[146:161], v[130:133], v[162:165], 0
	v_mfma_f32_32x32x16_bf16 v[130:145], v[134:137], v[162:165], 0
	ds_read_b128 v[234:237], v245 offset:0
	ds_read_b128 v[238:241], v245 offset:0x2000
	s_waitcnt lgkmcnt(4)
	v_mfma_f32_32x32x16_bf16 v[146:161], v[218:221], v[166:169], v[146:161]
	v_mfma_f32_32x32x16_bf16 v[130:145], v[222:225], v[166:169], v[130:145]
	ds_read_b128 v[218:221], v242 offset:0x80
	ds_read_b128 v[222:225], v242 offset:0x2080
	s_waitcnt lgkmcnt(4)
	v_mfma_f32_32x32x16_bf16 v[146:161], v[226:229], v[170:173], v[146:161]
	v_mfma_f32_32x32x16_bf16 v[130:145], v[230:233], v[170:173], v[130:145]
	ds_read_b128 v[226:229], v243 offset:0x80
	ds_read_b128 v[230:233], v243 offset:0x2080
	s_waitcnt lgkmcnt(4)
	v_mfma_f32_32x32x16_bf16 v[146:161], v[234:237], v[174:177], v[146:161]
	v_mfma_f32_32x32x16_bf16 v[130:145], v[238:241], v[174:177], v[130:145]
	ds_read_b128 v[234:237], v244 offset:0x80
	ds_read_b128 v[238:241], v244 offset:0x2080
	s_waitcnt lgkmcnt(4)
	v_mfma_f32_32x32x16_bf16 v[146:161], v[218:221], v[178:181], v[146:161]
	v_mfma_f32_32x32x16_bf16 v[130:145], v[222:225], v[178:181], v[130:145]
	ds_read_b128 v[218:221], v245 offset:0x80
	ds_read_b128 v[222:225], v245 offset:0x2080
	s_waitcnt lgkmcnt(4)
	v_mfma_f32_32x32x16_bf16 v[146:161], v[226:229], v[182:185], v[146:161]
	v_mfma_f32_32x32x16_bf16 v[130:145], v[230:233], v[182:185], v[130:145]
	s_waitcnt lgkmcnt(2)
	v_mfma_f32_32x32x16_bf16 v[146:161], v[234:237], v[186:189], v[146:161]
	v_mfma_f32_32x32x16_bf16 v[130:145], v[238:241], v[186:189], v[130:145]
	s_waitcnt lgkmcnt(0)
	v_mfma_f32_32x32x16_bf16 v[146:161], v[218:221], v[190:193], v[146:161]
	s_and_b64 vcc, exec, s[6:7]
	v_mfma_f32_32x32x16_bf16 v[130:145], v[222:225], v[190:193], v[130:145]
	s_cbranch_vccnz .LBB0_405
	s_waitcnt vmcnt(0)

.LBB0_423:
	ds_read_b64_tr_b16 v[146:147], v214 offset:0
	ds_read_b64_tr_b16 v[148:149], v214 offset:0x800
	ds_read_b64_tr_b16 v[150:151], v214 offset:0x1000
	ds_read_b64_tr_b16 v[152:153], v214 offset:0x1800
	ds_read_b64_tr_b16 v[154:155], v214 offset:0x2000
	ds_read_b64_tr_b16 v[156:157], v214 offset:0x2800
	ds_read_b64_tr_b16 v[158:159], v214 offset:0x3000
	ds_read_b64_tr_b16 v[160:161], v214 offset:0x3800
	s_waitcnt lgkmcnt(6)
	v_mfma_f32_32x32x16_bf16 v[114:129], v[130:133], v[146:149], v[114:129]
	ds_read_b64_tr_b16 v[222:223], v214 offset:0x200
	ds_read_b64_tr_b16 v[224:225], v214 offset:0xa00
	s_waitcnt lgkmcnt(6)
	v_mfma_f32_32x32x16_bf16 v[114:129], v[134:137], v[150:153], v[114:129]
	ds_read_b64_tr_b16 v[146:147], v214 offset:0x1200
	ds_read_b64_tr_b16 v[148:149], v214 offset:0x1a00
	s_waitcnt lgkmcnt(6)
	v_mfma_f32_32x32x16_bf16 v[114:129], v[138:141], v[154:157], v[114:129]
	ds_read_b64_tr_b16 v[150:151], v214 offset:0x2200
	ds_read_b64_tr_b16 v[152:153], v214 offset:0x2a00
	s_waitcnt lgkmcnt(6)
	v_mfma_f32_32x32x16_bf16 v[114:129], v[142:145], v[158:161], v[114:129]
	ds_read_b64_tr_b16 v[154:155], v214 offset:0x3200
	ds_read_b64_tr_b16 v[156:157], v214 offset:0x3a00
	s_waitcnt lgkmcnt(6)
	v_mfma_f32_32x32x16_bf16 v[98:113], v[130:133], v[222:225], v[98:113]
	ds_read_b64_tr_b16 v[158:159], v214 offset:0x400
	ds_read_b64_tr_b16 v[160:161], v214 offset:0xc00
	s_waitcnt lgkmcnt(6)
	v_mfma_f32_32x32x16_bf16 v[98:113], v[134:137], v[146:149], v[98:113]
	ds_read_b64_tr_b16 v[222:223], v214 offset:0x1400
	ds_read_b64_tr_b16 v[224:225], v214 offset:0x1c00
	s_waitcnt lgkmcnt(6)
	v_mfma_f32_32x32x16_bf16 v[98:113], v[138:141], v[150:153], v[98:113]
	ds_read_b64_tr_b16 v[146:147], v214 offset:0x2400
	ds_read_b64_tr_b16 v[148:149], v214 offset:0x2c00
	s_waitcnt lgkmcnt(6)
	v_mfma_f32_32x32x16_bf16 v[98:113], v[142:145], v[154:157], v[98:113]
	ds_read_b64_tr_b16 v[150:151], v214 offset:0x3400
	ds_read_b64_tr_b16 v[152:153], v214 offset:0x3c00
	s_waitcnt lgkmcnt(6)
	v_mfma_f32_32x32x16_bf16 v[82:97], v[130:133], v[158:161], v[82:97]
	ds_read_b64_tr_b16 v[154:155], v214 offset:0x600
	ds_read_b64_tr_b16 v[156:157], v214 offset:0xe00
	s_waitcnt lgkmcnt(6)
	v_mfma_f32_32x32x16_bf16 v[82:97], v[134:137], v[222:225], v[82:97]
	ds_read_b64_tr_b16 v[158:159], v214 offset:0x1600
	ds_read_b64_tr_b16 v[160:161], v214 offset:0x1e00
	s_waitcnt lgkmcnt(6)
	v_mfma_f32_32x32x16_bf16 v[82:97], v[138:141], v[146:149], v[82:97]
	ds_read_b64_tr_b16 v[222:223], v214 offset:0x2600
	ds_read_b64_tr_b16 v[224:225], v214 offset:0x2e00
	s_waitcnt lgkmcnt(6)
	v_mfma_f32_32x32x16_bf16 v[82:97], v[142:145], v[150:153], v[82:97]
	ds_read_b64_tr_b16 v[146:147], v214 offset:0x3600
	ds_read_b64_tr_b16 v[148:149], v214 offset:0x3e00
	s_waitcnt lgkmcnt(6)
	v_mfma_f32_32x32x16_bf16 v[66:81], v[130:133], v[154:157], v[66:81]
	ds_read_b64_tr_b16 v[150:151], v214 offset:0x4000
	ds_read_b64_tr_b16 v[152:153], v214 offset:0x4800
	s_waitcnt lgkmcnt(6)
	v_mfma_f32_32x32x16_bf16 v[66:81], v[134:137], v[158:161], v[66:81]
	ds_read_b64_tr_b16 v[154:155], v214 offset:0x5000
	ds_read_b64_tr_b16 v[156:157], v214 offset:0x5800
	s_waitcnt lgkmcnt(6)
	v_mfma_f32_32x32x16_bf16 v[66:81], v[138:141], v[222:225], v[66:81]
	ds_read_b64_tr_b16 v[158:159], v214 offset:0x6000
	ds_read_b64_tr_b16 v[160:161], v214 offset:0x6800
	s_waitcnt lgkmcnt(6)
	v_mfma_f32_32x32x16_bf16 v[66:81], v[142:145], v[146:149], v[66:81]
	ds_read_b64_tr_b16 v[222:223], v214 offset:0x7000
	ds_read_b64_tr_b16 v[224:225], v214 offset:0x7800
	s_waitcnt lgkmcnt(6)
	v_mfma_f32_32x32x16_bf16 v[50:65], v[130:133], v[150:153], v[50:65]
	ds_read_b64_tr_b16 v[146:147], v214 offset:0x4200
	ds_read_b64_tr_b16 v[148:149], v214 offset:0x4a00
	s_waitcnt lgkmcnt(6)
	v_mfma_f32_32x32x16_bf16 v[50:65], v[134:137], v[154:157], v[50:65]
	ds_read_b64_tr_b16 v[150:151], v214 offset:0x5200
	ds_read_b64_tr_b16 v[152:153], v214 offset:0x5a00
	s_waitcnt lgkmcnt(6)
	v_mfma_f32_32x32x16_bf16 v[50:65], v[138:141], v[158:161], v[50:65]
	ds_read_b64_tr_b16 v[154:155], v214 offset:0x6200
	ds_read_b64_tr_b16 v[156:157], v214 offset:0x6a00
	s_waitcnt lgkmcnt(6)
	v_mfma_f32_32x32x16_bf16 v[50:65], v[142:145], v[222:225], v[50:65]
	ds_read_b64_tr_b16 v[158:159], v214 offset:0x7200
	ds_read_b64_tr_b16 v[160:161], v214 offset:0x7a00
	s_waitcnt lgkmcnt(6)
	v_mfma_f32_32x32x16_bf16 v[34:49], v[130:133], v[146:149], v[34:49]
	ds_read_b64_tr_b16 v[222:223], v214 offset:0x4400
	ds_read_b64_tr_b16 v[224:225], v214 offset:0x4c00
	s_waitcnt lgkmcnt(6)
	v_mfma_f32_32x32x16_bf16 v[34:49], v[134:137], v[150:153], v[34:49]
	ds_read_b64_tr_b16 v[146:147], v214 offset:0x5400
	ds_read_b64_tr_b16 v[148:149], v214 offset:0x5c00
	s_waitcnt lgkmcnt(6)
	v_mfma_f32_32x32x16_bf16 v[34:49], v[138:141], v[154:157], v[34:49]
	ds_read_b64_tr_b16 v[150:151], v214 offset:0x6400
	ds_read_b64_tr_b16 v[152:153], v214 offset:0x6c00
	s_waitcnt lgkmcnt(6)
	v_mfma_f32_32x32x16_bf16 v[34:49], v[142:145], v[158:161], v[34:49]
	ds_read_b64_tr_b16 v[154:155], v214 offset:0x7400
	ds_read_b64_tr_b16 v[156:157], v214 offset:0x7c00
	s_waitcnt lgkmcnt(6)
	v_mfma_f32_32x32x16_bf16 v[18:33], v[130:133], v[222:225], v[18:33]
	ds_read_b64_tr_b16 v[158:159], v214 offset:0x4600
	ds_read_b64_tr_b16 v[160:161], v214 offset:0x4e00
	s_waitcnt lgkmcnt(6)
	v_mfma_f32_32x32x16_bf16 v[18:33], v[134:137], v[146:149], v[18:33]
	ds_read_b64_tr_b16 v[222:223], v214 offset:0x5600
	ds_read_b64_tr_b16 v[224:225], v214 offset:0x5e00
	s_waitcnt lgkmcnt(6)
	v_mfma_f32_32x32x16_bf16 v[18:33], v[138:141], v[150:153], v[18:33]
	ds_read_b64_tr_b16 v[146:147], v214 offset:0x6600
	ds_read_b64_tr_b16 v[148:149], v214 offset:0x6e00
	s_waitcnt lgkmcnt(6)
	v_mfma_f32_32x32x16_bf16 v[18:33], v[142:145], v[154:157], v[18:33]
	ds_read_b64_tr_b16 v[150:151], v214 offset:0x7600
	ds_read_b64_tr_b16 v[152:153], v214 offset:0x7e00
	s_waitcnt lgkmcnt(6)
	v_mfma_f32_32x32x16_bf16 v[2:17], v[130:133], v[158:161], v[2:17]
	s_waitcnt lgkmcnt(4)
	v_mfma_f32_32x32x16_bf16 v[2:17], v[134:137], v[222:225], v[2:17]
	s_waitcnt lgkmcnt(2)
	v_mfma_f32_32x32x16_bf16 v[2:17], v[138:141], v[146:149], v[2:17]
	s_waitcnt lgkmcnt(0)
	v_mfma_f32_32x32x16_bf16 v[2:17], v[142:145], v[150:153], v[2:17]
	v_add_u32_e32 v221, s38, v208
	ds_read_b128 v[130:133], v221 offset:0
	ds_read_b128 v[134:137], v221 offset:0x2000
	v_add_u32_e32 v246, s38, v209
	ds_read_b128 v[222:225], v246 offset:0
	ds_read_b128 v[226:229], v246 offset:0x2000
	v_add_u32_e32 v247, s38, v210
	ds_read_b128 v[230:233], v247 offset:0
	ds_read_b128 v[234:237], v247 offset:0x2000
	s_waitcnt lgkmcnt(4)
	v_add_u32_e32 v248, s38, v211
	v_mfma_f32_32x32x16_bf16 v[146:161], v[130:133], v[162:165], 0
	v_mfma_f32_32x32x16_bf16 v[130:145], v[134:137], v[162:165], 0
	ds_read_b128 v[238:241], v248 offset:0
	ds_read_b128 v[242:245], v248 offset:0x2000
	s_waitcnt lgkmcnt(4)
	v_mfma_f32_32x32x16_bf16 v[146:161], v[222:225], v[166:169], v[146:161]
	v_mfma_f32_32x32x16_bf16 v[130:145], v[226:229], v[166:169], v[130:145]
	ds_read_b128 v[222:225], v221 offset:0x80
	ds_read_b128 v[226:229], v221 offset:0x2080
	s_waitcnt lgkmcnt(4)
	v_mfma_f32_32x32x16_bf16 v[146:161], v[230:233], v[170:173], v[146:161]
	v_mfma_f32_32x32x16_bf16 v[130:145], v[234:237], v[170:173], v[130:145]
	ds_read_b128 v[230:233], v246 offset:0x80
	ds_read_b128 v[234:237], v246 offset:0x2080
	s_waitcnt lgkmcnt(4)
	v_mfma_f32_32x32x16_bf16 v[146:161], v[238:241], v[174:177], v[146:161]
	v_mfma_f32_32x32x16_bf16 v[130:145], v[242:245], v[174:177], v[130:145]
	ds_read_b128 v[238:241], v247 offset:0x80
	ds_read_b128 v[242:245], v247 offset:0x2080
	s_waitcnt lgkmcnt(4)
	v_mfma_f32_32x32x16_bf16 v[146:161], v[222:225], v[178:181], v[146:161]
	v_mfma_f32_32x32x16_bf16 v[130:145], v[226:229], v[178:181], v[130:145]
	ds_read_b128 v[222:225], v248 offset:0x80
	ds_read_b128 v[226:229], v248 offset:0x2080
	s_waitcnt lgkmcnt(4)
	v_mfma_f32_32x32x16_bf16 v[146:161], v[230:233], v[182:185], v[146:161]
	v_mfma_f32_32x32x16_bf16 v[130:145], v[234:237], v[182:185], v[130:145]
	s_waitcnt lgkmcnt(2)
	v_mfma_f32_32x32x16_bf16 v[146:161], v[238:241], v[186:189], v[146:161]
	v_mfma_f32_32x32x16_bf16 v[130:145], v[242:245], v[186:189], v[130:145]
	s_waitcnt lgkmcnt(0)
	v_mfma_f32_32x32x16_bf16 v[146:161], v[222:225], v[190:193], v[146:161]
	s_and_b64 vcc, exec, s[6:7]
	v_mfma_f32_32x32x16_bf16 v[130:145], v[226:229], v[190:193], v[130:145]
	s_cbranch_vccnz .LBB0_425
	s_waitcnt vmcnt(0)
